# top-k rank loop: one 64-bit key compare per candidate (value bits, 63-lane) instead of gt/eq/index triple
# speedup vs baseline: 1.0317x; 1.0075x over previous
.LBB0_1297:
	s_add_i32 s7, s6, s77
	s_mul_i32 s16, s7, 0x104
	v_add_u32_e32 v35, s16, v34
	ds_read2st64_b32 v[36:37], v35 offset1:65
	s_mov_b32 s24, 0
	s_waitcnt lgkmcnt(0)
	v_add_f32_e32 v38, v36, v37
	ds_read2st64_b32 v[36:37], v35 offset0:130 offset1:195
	s_waitcnt lgkmcnt(0)
	v_add_f32_e32 v35, v38, v36
	v_add_f32_e32 v35, v35, v37
	v_mov_b32_e32 v36, 0x461c4000
	v_cndmask_b32_e64 v35, v35, v36, s[10:11]
	v_mov_b32_e32 v36, 0
	v_cndmask_b32_e64 v39, v35, v36, s[12:13]
	v_sub_u32_e32 v38, 63, v0
	v_mov_b32_e32 v36, 0
.LBB0_1298:
	s_sub_i32 s18, 63, s24
	v_readlane_b32 s19, v39, s24
	s_add_i32 s78, s24, 1
	s_sub_i32 s16, 63, s78
	v_readlane_b32 s17, v39, s78
	s_nop 0
	v_cmp_gt_u64_e64 s[20:21], s[18:19], v[38:39]
	s_add_i32 s78, s24, 2
	s_sub_i32 s18, 63, s78
	v_readlane_b32 s19, v39, s78
	v_addc_co_u32_e64 v36, s[20:21], 0, v36, s[20:21]
	v_cmp_gt_u64_e64 s[20:21], s[16:17], v[38:39]
	s_add_i32 s78, s24, 3
	s_sub_i32 s16, 63, s78
	v_readlane_b32 s17, v39, s78
	v_addc_co_u32_e64 v36, s[20:21], 0, v36, s[20:21]
	v_cmp_gt_u64_e64 s[20:21], s[18:19], v[38:39]
	s_add_i32 s78, s24, 4
	s_sub_i32 s18, 63, s78
	v_readlane_b32 s19, v39, s78
	v_addc_co_u32_e64 v36, s[20:21], 0, v36, s[20:21]
	v_cmp_gt_u64_e64 s[20:21], s[16:17], v[38:39]
	s_add_i32 s78, s24, 5
	s_sub_i32 s16, 63, s78
	v_readlane_b32 s17, v39, s78
	v_addc_co_u32_e64 v36, s[20:21], 0, v36, s[20:21]
	v_cmp_gt_u64_e64 s[20:21], s[18:19], v[38:39]
	s_add_i32 s78, s24, 6
	s_sub_i32 s18, 63, s78
	v_readlane_b32 s19, v39, s78
	v_addc_co_u32_e64 v36, s[20:21], 0, v36, s[20:21]
	v_cmp_gt_u64_e64 s[20:21], s[16:17], v[38:39]
	s_add_i32 s78, s24, 7
	s_sub_i32 s16, 63, s78
	v_readlane_b32 s17, v39, s78
	v_addc_co_u32_e64 v36, s[20:21], 0, v36, s[20:21]
	v_cmp_gt_u64_e64 s[20:21], s[18:19], v[38:39]
	s_nop 1
	v_addc_co_u32_e64 v36, s[20:21], 0, v36, s[20:21]
	v_cmp_gt_u64_e64 s[20:21], s[16:17], v[38:39]
	s_nop 1
	v_addc_co_u32_e64 v36, s[20:21], 0, v36, s[20:21]
	s_add_i32 s24, s24, 8
	s_cmp_gt_u32 s24, s27
	s_cbranch_scc0 .LBB0_1298
	v_cmp_gt_u32_e64 s[16:17], 16, v36
	s_and_b64 s[16:17], s[16:17], s[14:15]
	s_nop 0
	v_cndmask_b32_e64 v35, 0, 1, s[16:17]
	v_cmp_ne_u32_e64 s[16:17], 0, v35
	s_and_saveexec_b64 s[18:19], vcc
	s_cbranch_execz .LBB0_1296
	s_lshl_b32 s7, s7, 3
	s_add_i32 s7, s7, 0
	s_add_i32 s7, s7, 0x10800
	v_mov_b32_e32 v35, s7
	v_mov_b64_e32 v[36:37], s[16:17]
	ds_write_b64 v35, v[36:37]
	s_branch .LBB0_1296
